# prologue de-serialisation applied to the fifth (RET dual) GEMM too; NAT local-tile loop exponent as one fma per element
# speedup vs baseline: 1.0107x; 1.0037x over previous
; #define PG8_STAGE(bufoff, gbase, voff) do { _Pragma("unroll") for (int _i = 0; _i < 2; ++_i) \
;         __builtin_amdgcn_global_load_lds((const unsigned*)((const char*)(gbase) + (voff)[_i]), (LAS unsigned*)(lds + (bufoff) + ldsw + _i * 8192), 16, 0, 0); } while (0)
; #define PG8_WAIT_V(n) asm volatile("s_waitcnt vmcnt(" #n ")" ::: "memory")
; #define PG8_BAR __builtin_amdgcn_s_barrier()
; template <class Epi>
; DI void gemm_phase(LAS unsigned char* lds, const Gemm g, const StaticOrder S, const Epi E) {
;     ...
;     PG8_STAGE(PG8_SB(0, 0), cB, voffB); PG8_STAGE(PG8_SB(0, 1), cB + hstepB, voffB); PG8_STAGE(PG8_SA(0, 0), cA, voffA); PG8_STAGE(PG8_SA(0, 1), cA + hstepA, voffA);
;     if (wr == 1) PG8_BAR;
;     PG8_WAIT_V(2); PG8_BAR;
;     PG8_STAGE(PG8_SB(1, 0), cB + kstep, voffB); PG8_STAGE(PG8_SA(1, 0), cA + kstep, voffA); PG8_STAGE(PG8_SB(1, 1), cB + hstepB + kstep, voffB);
;     PG8_WAIT_V(6); PG8_BAR;
.LBB0_219:
	s_and_b32 s20, s22, 3
	s_lshl_b32 s70, s23, 6
	s_lshl_b32 s26, s23, 13
	s_lshl_b32 s71, s20, 5
	s_lshl_b32 s27, s20, 12
	s_add_u32 s22, s38, 0xb8200
	s_addc_u32 s23, s39, 0
	s_add_i32 m0, s57, 0x18000
	v_lshl_add_u64 v[6:7], v[6:7], 0, s[94:95]
	global_load_lds_dwordx4 v[6:7], off
	v_lshl_add_u64 v[4:5], v[4:5], 0, s[94:95]
	s_add_i32 m0, s57, 0x1a000
	s_add_i32 s72, s57, 0x8000
	s_add_i32 s73, s57, 0xa000
	global_load_lds_dwordx4 v[4:5], off
	v_lshl_add_u64 v[0:1], v[0:1], 0, s[94:95]
	s_mov_b32 m0, s72
	s_add_u32 s20, s30, 0x40080
	global_load_lds_dwordx4 v[0:1], off
	v_lshl_add_u64 v[0:1], v[2:3], 0, s[94:95]
	s_mov_b32 m0, s73
	s_addc_u32 s21, s31, 0
	global_load_lds_dwordx4 v[0:1], off
	s_add_i32 m0, s57, 0x1c000
	v_lshl_add_u64 v[0:1], s[20:21], 0, v[160:161]
	global_load_lds_dwordx4 v[0:1], off
	v_lshl_add_u64 v[0:1], s[20:21], 0, v[164:165]
	s_add_i32 m0, s57, 0x1e000
	v_bfe_u32 v182, v8, 4, 2
	global_load_lds_dwordx4 v[0:1], off
	s_waitcnt vmcnt(8)
	s_barrier
	v_and_b32_e32 v157, 15, v8
	v_lshlrev_b32_e32 v0, 4, v182
	v_lshlrev_b32_e32 v1, 2, v8
	v_lshl_or_b32 v0, v157, 6, v0
	v_and_b32_e32 v1, 32, v1
	v_bitop3_b32 v2, v0, s26, v1 bitop3:0xde
	v_bitop3_b32 v183, v0, s27, v1 bitop3:0xde
	v_lshlrev_b32_e32 v0, 14, v9
	v_and_b32_e32 v0, 0xffff8000, v0
	v_lshl_add_u32 v0, v10, 11, v0
	v_and_b32_e32 v1, 1, v9
	v_lshl_or_b32 v0, v1, 6, v0
	v_lshl_add_u32 v166, v11, 1, v0
	v_lshlrev_b32_e32 v0, 14, v12
	v_and_b32_e32 v0, 0xffff8000, v0
	s_waitcnt vmcnt(6)
	s_cmpk_lt_u32 s40, 0x100
	v_lshl_add_u32 v0, v13, 11, v0
	v_and_b32_e32 v1, 1, v12
	s_cselect_b64 s[46:47], -1, 0
	s_bitcmp0_b32 s40, 6
	v_lshl_or_b32 v0, v1, 6, v0
	s_mov_b32 s75, 0
	s_cselect_b64 s[40:41], -1, 0
	v_mov_b32_e32 v167, v147
	v_lshl_add_u32 v168, v14, 1, v0
	v_mov_b32_e32 v169, v147
	v_add_u32_e32 v184, 0, v2
	s_barrier
	s_branch .LBB0_222
